# speedup vs baseline: 1.0066x; 1.0045x over previous
; template <int MODE>
; __device__ __forceinline__ void attn_item(const Params& P, int b, int h, int qb, char* lds) {
;     ...
;       if (!(started && __all(pmax < -160.f))) {
;       float alpha = 1.f;
;       if (!started || __any(pmax > 6.f)) {
;         float delta = started ? fmaxf(pmax, 0.f) : pmax;
;         if (!(delta > -1e30f)) delta = 0.f;
;         if (started) alpha = __builtin_amdgcn_exp2f(-delta);
;         m_reg += delta;
; #pragma unroll
;         for (int r = 0; r < 16; ++r) { p0[r] -= delta; p1[r] -= delta; }
;         started = 1;
;       }
; #pragma unroll
;       for (int r = 0; r < 16; ++r) { p0[r] = __builtin_amdgcn_exp2f(p0[r]); p1[r] = __builtin_amdgcn_exp2f(p1[r]); }
.Lmy_fast0:
	s_mov_b64 s[34:35], -1
	v_mov_b32_e32 v0, 1.0
	s_branch .LBB0_693

; template <int MODE>
; __device__ __forceinline__ void attn_item(const Params& P, int b, int h, int qb, char* lds) {
;     ...
;       float pmax = p0[0];
; #pragma unroll
;       for (int r = 1; r < 16; ++r) pmax = fmaxf(pmax, p0[r]);
; #pragma unroll
;       for (int r = 0; r < 16; ++r) pmax = fmaxf(pmax, p1[r]);
;       pmax = fmaxf(pmax, __shfl_xor(pmax, 32));
;       if (!(started && __all(pmax < -160.f))) {
;       float alpha = 1.f;
;       if (!started || __any(pmax > 6.f)) {
.LBB0_1027:
	s_nop 9
	v_max_f32_e32 v0, v97, v97
	v_max_f32_e32 v2, v96, v96
	v_max_f32_e32 v0, v2, v0
	v_max3_f32 v0, v0, v98, v99
	v_max3_f32 v0, v0, v100, v101
	v_max3_f32 v0, v0, v102, v103
	v_max3_f32 v0, v0, v104, v105
	v_max3_f32 v0, v0, v106, v107
	v_max3_f32 v0, v0, v108, v109
	v_max3_f32 v0, v0, v110, v111
	v_max3_f32 v0, v0, v112, v113
	v_max3_f32 v0, v0, v114, v115
	v_max3_f32 v0, v0, v116, v117
	v_max3_f32 v0, v0, v118, v119
	v_max3_f32 v0, v0, v120, v121
	v_max3_f32 v0, v0, v122, v123
	v_max3_f32 v0, v0, v124, v125
	v_max3_f32 v0, v0, v126, v127
	v_mov_b32_e32 v2, v0
	s_nop 1
	v_permlane32_swap_b32_e32 v0, v2
	s_cmp_eq_u32 s38, 0
	s_cselect_b64 s[10:11], -1, 0
	s_cmp_lg_u32 s38, 0
	v_max_f32_e32 v0, v0, v2
	s_cbranch_scc0 .LBB0_1033
	v_cmp_gt_f32_e32 vcc, s59, v0
	s_mov_b64 s[40:41], 0
	s_cmp_lg_u64 vcc, exec
	s_mov_b64 s[38:39], 0
	s_mov_b64 s[42:43], 0
	s_cbranch_scc0 .LBB0_1034
	v_cmp_lt_f32_e32 vcc, s60, v0
	s_cbranch_vccz .Lmy_fast1
	v_max_f32_e32 v2, v0, v0
	v_max_f32_e32 v2, 0, v2
	s_mov_b64 s[42:43], -1
	s_and_b64 vcc, exec, s[40:41]
	s_cbranch_vccnz .LBB0_1035

; template <int MODE>
; __device__ __forceinline__ void attn_item(const Params& P, int b, int h, int qb, char* lds) {
;     ...
;       if (!(started && __all(pmax < -160.f))) {
;       float alpha = 1.f;
;       if (!started || __any(pmax > 6.f)) {
;         float delta = started ? fmaxf(pmax, 0.f) : pmax;
;         if (!(delta > -1e30f)) delta = 0.f;
;         if (started) alpha = __builtin_amdgcn_exp2f(-delta);
;         m_reg += delta;
; #pragma unroll
;         for (int r = 0; r < 16; ++r) { p0[r] -= delta; p1[r] -= delta; }
;         started = 1;
;       }
; #pragma unroll
;       for (int r = 0; r < 16; ++r) { p0[r] = __builtin_amdgcn_exp2f(p0[r]); p1[r] = __builtin_amdgcn_exp2f(p1[r]); }
.Lmy_fast1:
	s_mov_b64 s[38:39], -1
	v_mov_b32_e32 v0, 1.0
	s_branch .LBB0_1037
